# S5 helper: forcing terms laid out [tt][state][re,im] in LDS, scan lane fetches two steps with one ds_read2st64_b64 (8 reads per chunk instead of 16)
# baseline (speedup 1.0000x reference)
.LBB0_398:
	s_or_b64 exec, exec, s[38:39]
	v_lshl_or_b32 v2, s8, 10, v142
	v_mov_b32_e32 v3, v0
	v_lshl_add_u64 v[2:3], v[68:69], 0, v[2:3]
	global_load_ushort v212, v[2:3], off
	global_load_ushort v213, v[2:3], off offset:1024
	global_load_ushort v214, v[2:3], off offset:2048
	global_load_ushort v215, v[2:3], off offset:3072
	v_add_u32_e32 v91, v143, v102
	ds_read_b128 v[92:95], v91 offset:12544
	ds_read_b128 v[164:167], v91 offset:13056
	ds_read_b128 v[216:219], v91 offset:13568
	ds_read_b128 v[220:223], v146 offset:12544
	ds_read_b128 v[224:227], v91 offset:14592
	ds_read_b128 v[228:231], v91 offset:15104
	ds_read_b128 v[244:247], v91 offset:15616
	ds_read_b128 v[248:251], v147 offset:12544
	v_and_b32_e32 v96, 15, v98
	v_lshl_add_u32 v96, v96, 2, v138
	v_add_u32_e32 v96, 0xf300, v96
	v_add_u32_e32 v97, 0x400, v96
	s_andn2_b64 vcc, exec, s[50:51]
	s_waitcnt lgkmcnt(7)
	v_mfma_f32_16x16x32_bf16 v[92:95], v[12:15], v[92:95], 0
	s_waitcnt lgkmcnt(6)
	v_mfma_f32_16x16x32_bf16 v[164:167], v[12:15], v[164:167], 0
	s_waitcnt lgkmcnt(5)
	v_mfma_f32_16x16x32_bf16 v[216:219], v[12:15], v[216:219], 0
	s_waitcnt lgkmcnt(4)
	v_mfma_f32_16x16x32_bf16 v[220:223], v[12:15], v[220:223], 0
	s_waitcnt lgkmcnt(3)
	v_mfma_f32_16x16x32_bf16 v[224:227], v[12:15], v[224:227], 0
	s_waitcnt lgkmcnt(2)
	v_mfma_f32_16x16x32_bf16 v[228:231], v[12:15], v[228:231], 0
	s_waitcnt lgkmcnt(1)
	v_mfma_f32_16x16x32_bf16 v[244:247], v[12:15], v[244:247], 0
	s_waitcnt lgkmcnt(0)
	v_mfma_f32_16x16x32_bf16 v[248:251], v[12:15], v[248:251], 0
	s_nop 1
	ds_write2_b32 v96, v92, v224 offset0:0 offset1:1
	ds_write2_b32 v96, v93, v225 offset0:128 offset1:129
	ds_write2_b32 v97, v94, v226 offset0:0 offset1:1
	ds_write2_b32 v97, v95, v227 offset0:128 offset1:129
	ds_write2_b32 v96, v164, v228 offset0:32 offset1:33
	ds_write2_b32 v96, v165, v229 offset0:160 offset1:161
	ds_write2_b32 v97, v166, v230 offset0:32 offset1:33
	ds_write2_b32 v97, v167, v231 offset0:160 offset1:161
	ds_write2_b32 v96, v216, v244 offset0:64 offset1:65
	ds_write2_b32 v96, v217, v245 offset0:192 offset1:193
	ds_write2_b32 v97, v218, v246 offset0:64 offset1:65
	ds_write2_b32 v97, v219, v247 offset0:192 offset1:193
	ds_write2_b32 v96, v220, v248 offset0:96 offset1:97
	ds_write2_b32 v96, v221, v249 offset0:224 offset1:225
	ds_write2_b32 v97, v222, v250 offset0:96 offset1:97
	ds_write2_b32 v97, v223, v251 offset0:224 offset1:225
	s_waitcnt lgkmcnt(0)
	v_lshl_add_u32 v91, v98, 1, v141
	v_add_u32_e32 v96, 0x2000, v91
	v_add_u32_e32 v97, 0x2440, v91
	v_add_u32_e32 v159, 0x2880, v91
	v_add_u32_e32 v91, 0x2cc0, v91
	v_lshl_add_u32 v160, v98, 2, v140
	ds_read2st64_b64 v[216:219], v160 offset1:1
	ds_read2st64_b64 v[220:223], v160 offset0:2 offset1:3
	ds_read2st64_b64 v[224:227], v160 offset0:4 offset1:5
	ds_read2st64_b64 v[228:231], v160 offset0:6 offset1:7
	ds_read2st64_b64 v[244:247], v160 offset0:8 offset1:9
	ds_read2st64_b64 v[248:251], v160 offset0:10 offset1:11
	ds_read2st64_b64 v[92:95], v160 offset0:12 offset1:13
	ds_read2st64_b64 v[164:167], v160 offset0:14 offset1:15
	s_waitcnt lgkmcnt(7)
	v_pk_fma_f32 v[14:15], v[64:65], v[60:61], v[216:217] op_sel:[0,1,0] op_sel_hi:[0,0,1] neg_lo:[1,0,0]
	v_pk_fma_f32 v[60:61], v[56:57], v[60:61], v[14:15] op_sel_hi:[0,1,1]
	v_cvt_pk_bf16_f32 v12, v60, v61
	s_waitcnt lgkmcnt(7)
	v_pk_fma_f32 v[14:15], v[64:65], v[60:61], v[218:219] op_sel:[0,1,0] op_sel_hi:[0,0,1] neg_lo:[1,0,0]
	v_pk_fma_f32 v[60:61], v[56:57], v[60:61], v[14:15] op_sel_hi:[0,1,1]
	v_cvt_pk_bf16_f32 v13, v60, v61
	ds_write2_b32 v96, v12, v13 offset0:0 offset1:68
	s_waitcnt lgkmcnt(7)
	v_pk_fma_f32 v[14:15], v[64:65], v[60:61], v[220:221] op_sel:[0,1,0] op_sel_hi:[0,0,1] neg_lo:[1,0,0]
	v_pk_fma_f32 v[60:61], v[56:57], v[60:61], v[14:15] op_sel_hi:[0,1,1]
	v_cvt_pk_bf16_f32 v12, v60, v61
	s_waitcnt lgkmcnt(7)
	v_pk_fma_f32 v[14:15], v[64:65], v[60:61], v[222:223] op_sel:[0,1,0] op_sel_hi:[0,0,1] neg_lo:[1,0,0]
	v_pk_fma_f32 v[60:61], v[56:57], v[60:61], v[14:15] op_sel_hi:[0,1,1]
	v_cvt_pk_bf16_f32 v13, v60, v61
	ds_write2_b32 v96, v12, v13 offset0:136 offset1:204
	s_waitcnt lgkmcnt(7)
	v_pk_fma_f32 v[14:15], v[64:65], v[60:61], v[224:225] op_sel:[0,1,0] op_sel_hi:[0,0,1] neg_lo:[1,0,0]
	v_pk_fma_f32 v[60:61], v[56:57], v[60:61], v[14:15] op_sel_hi:[0,1,1]
	v_cvt_pk_bf16_f32 v12, v60, v61
	s_waitcnt lgkmcnt(7)
	v_pk_fma_f32 v[14:15], v[64:65], v[60:61], v[226:227] op_sel:[0,1,0] op_sel_hi:[0,0,1] neg_lo:[1,0,0]
	v_pk_fma_f32 v[60:61], v[56:57], v[60:61], v[14:15] op_sel_hi:[0,1,1]
	v_cvt_pk_bf16_f32 v13, v60, v61
	ds_write2_b32 v97, v12, v13 offset0:0 offset1:68
	s_waitcnt lgkmcnt(7)
	v_pk_fma_f32 v[14:15], v[64:65], v[60:61], v[228:229] op_sel:[0,1,0] op_sel_hi:[0,0,1] neg_lo:[1,0,0]
	v_pk_fma_f32 v[60:61], v[56:57], v[60:61], v[14:15] op_sel_hi:[0,1,1]
	v_cvt_pk_bf16_f32 v12, v60, v61
	s_waitcnt lgkmcnt(7)
	v_pk_fma_f32 v[14:15], v[64:65], v[60:61], v[230:231] op_sel:[0,1,0] op_sel_hi:[0,0,1] neg_lo:[1,0,0]
	v_pk_fma_f32 v[60:61], v[56:57], v[60:61], v[14:15] op_sel_hi:[0,1,1]
	v_cvt_pk_bf16_f32 v13, v60, v61
	ds_write2_b32 v97, v12, v13 offset0:136 offset1:204
	s_waitcnt lgkmcnt(7)
	v_pk_fma_f32 v[14:15], v[64:65], v[60:61], v[244:245] op_sel:[0,1,0] op_sel_hi:[0,0,1] neg_lo:[1,0,0]
	v_pk_fma_f32 v[60:61], v[56:57], v[60:61], v[14:15] op_sel_hi:[0,1,1]
	v_cvt_pk_bf16_f32 v12, v60, v61
	s_waitcnt lgkmcnt(7)
	v_pk_fma_f32 v[14:15], v[64:65], v[60:61], v[246:247] op_sel:[0,1,0] op_sel_hi:[0,0,1] neg_lo:[1,0,0]
	v_pk_fma_f32 v[60:61], v[56:57], v[60:61], v[14:15] op_sel_hi:[0,1,1]
	v_cvt_pk_bf16_f32 v13, v60, v61
	ds_write2_b32 v159, v12, v13 offset0:0 offset1:68
	s_waitcnt lgkmcnt(7)
	v_pk_fma_f32 v[14:15], v[64:65], v[60:61], v[248:249] op_sel:[0,1,0] op_sel_hi:[0,0,1] neg_lo:[1,0,0]
	v_pk_fma_f32 v[60:61], v[56:57], v[60:61], v[14:15] op_sel_hi:[0,1,1]
	v_cvt_pk_bf16_f32 v12, v60, v61
	s_waitcnt lgkmcnt(7)
	v_pk_fma_f32 v[14:15], v[64:65], v[60:61], v[250:251] op_sel:[0,1,0] op_sel_hi:[0,0,1] neg_lo:[1,0,0]
	v_pk_fma_f32 v[60:61], v[56:57], v[60:61], v[14:15] op_sel_hi:[0,1,1]
	v_cvt_pk_bf16_f32 v13, v60, v61
	ds_write2_b32 v159, v12, v13 offset0:136 offset1:204
	s_waitcnt lgkmcnt(7)
	v_pk_fma_f32 v[14:15], v[64:65], v[60:61], v[92:93] op_sel:[0,1,0] op_sel_hi:[0,0,1] neg_lo:[1,0,0]
	v_pk_fma_f32 v[60:61], v[56:57], v[60:61], v[14:15] op_sel_hi:[0,1,1]
	v_cvt_pk_bf16_f32 v12, v60, v61
	s_waitcnt lgkmcnt(7)
	v_pk_fma_f32 v[14:15], v[64:65], v[60:61], v[94:95] op_sel:[0,1,0] op_sel_hi:[0,0,1] neg_lo:[1,0,0]
	v_pk_fma_f32 v[60:61], v[56:57], v[60:61], v[14:15] op_sel_hi:[0,1,1]
	v_cvt_pk_bf16_f32 v13, v60, v61
	ds_write2_b32 v91, v12, v13 offset0:0 offset1:68
	s_waitcnt lgkmcnt(7)
	v_pk_fma_f32 v[14:15], v[64:65], v[60:61], v[164:165] op_sel:[0,1,0] op_sel_hi:[0,0,1] neg_lo:[1,0,0]
	v_pk_fma_f32 v[60:61], v[56:57], v[60:61], v[14:15] op_sel_hi:[0,1,1]
	v_cvt_pk_bf16_f32 v12, v60, v61
	s_waitcnt lgkmcnt(7)
	v_pk_fma_f32 v[14:15], v[64:65], v[60:61], v[166:167] op_sel:[0,1,0] op_sel_hi:[0,0,1] neg_lo:[1,0,0]
	v_pk_fma_f32 v[60:61], v[56:57], v[60:61], v[14:15] op_sel_hi:[0,1,1]
	v_cvt_pk_bf16_f32 v13, v60, v61
	ds_write2_b32 v91, v12, v13 offset0:136 offset1:204
	s_waitcnt lgkmcnt(0)
	ds_read_b128 v[12:15], v144 offset:8192
	ds_read_b128 v[92:95], v145 offset:16640
	ds_read_b128 v[216:219], v144 offset:8256
	ds_read_b128 v[220:223], v145 offset:16704
	ds_read_b128 v[224:227], v144 offset:8320
	ds_read_b128 v[228:231], v145 offset:16768
	ds_read_b128 v[244:247], v144 offset:8384
	ds_read_b128 v[248:251], v145 offset:16832
	s_waitcnt lgkmcnt(6)
	v_mfma_f32_16x16x32_bf16 v[12:15], v[12:15], v[92:95], 0
	s_waitcnt lgkmcnt(4)
	v_mfma_f32_16x16x32_bf16 v[12:15], v[216:219], v[220:223], v[12:15]
	s_waitcnt lgkmcnt(2)
	v_mfma_f32_16x16x32_bf16 v[12:15], v[224:227], v[228:231], v[12:15]
	s_waitcnt lgkmcnt(0)
	v_mfma_f32_16x16x32_bf16 v[12:15], v[244:247], v[248:251], v[12:15]
	s_nop 7
	s_waitcnt vmcnt(0)
	v_lshlrev_b32_e32 v88, 16, v212
	v_lshlrev_b32_e32 v89, 16, v213
	v_lshlrev_b32_e32 v90, 16, v214
	v_lshlrev_b32_e32 v91, 16, v215
	v_pk_fma_f32 v[12:13], v[148:149], v[88:89], v[12:13] op_sel_hi:[0,1,1]
	v_pk_fma_f32 v[14:15], v[148:149], v[90:91], v[14:15] op_sel_hi:[0,1,1]
	v_mov_b32_e32 v88, 0x3dd2d3e8
	v_mov_b32_e32 v90, 0x40135761
	v_pk_mul_f32 v[92:93], v[12:13], v[12:13]
	v_pk_mul_f32 v[94:95], v[14:15], v[14:15]
	v_pk_fma_f32 v[92:93], v[92:93], v[88:89], v[90:91] op_sel_hi:[1,0,0]
	v_pk_fma_f32 v[94:95], v[94:95], v[88:89], v[90:91] op_sel_hi:[1,0,0]
	v_pk_mul_f32 v[92:93], v[92:93], v[12:13]
	v_pk_mul_f32 v[94:95], v[94:95], v[14:15]
	v_mov_b32_e32 v88, 1.0
	v_exp_f32_e32 v92, v92
	v_exp_f32_e32 v93, v93
	v_exp_f32_e32 v94, v94
	v_exp_f32_e32 v95, v95
	s_nop 0
	v_pk_add_f32 v[92:93], v[92:93], v[88:89] op_sel_hi:[1,0]
	v_pk_add_f32 v[94:95], v[94:95], v[88:89] op_sel_hi:[1,0]
	v_rcp_f32_e32 v92, v92
	v_rcp_f32_e32 v93, v93
	v_rcp_f32_e32 v94, v94
	v_rcp_f32_e32 v95, v95
	s_nop 0
	v_pk_fma_f32 v[12:13], v[12:13], v[92:93], v[12:13] neg_lo:[1,0,0] neg_hi:[1,0,0]
	v_pk_fma_f32 v[14:15], v[14:15], v[94:95], v[14:15] neg_lo:[1,0,0] neg_hi:[1,0,0]
	v_cvt_pk_bf16_f32 v12, v12, v13
	v_cvt_pk_bf16_f32 v14, v14, v15
	global_store_short v[2:3], v12, off
	global_store_short_d16_hi v[2:3], v12, off offset:1024
	global_store_short v[2:3], v14, off offset:2048
	global_store_short_d16_hi v[2:3], v14, off offset:3072
	s_waitcnt lgkmcnt(0)
	v_lshlrev_b32_e32 v1, 2, v128
	s_cbranch_vccnz .LBB0_408
	s_waitcnt vmcnt(4)
	v_lshlrev_b32_e32 v16, 16, v176
	v_lshlrev_b32_e32 v30, 16, v177
	v_lshlrev_b32_e32 v32, 16, v178
	v_lshlrev_b32_e32 v36, 16, v179
	v_lshlrev_b32_e32 v17, 16, v180
	v_lshlrev_b32_e32 v26, 16, v181
	v_lshlrev_b32_e32 v27, 16, v182
	v_lshlrev_b32_e32 v28, 16, v183
	v_lshlrev_b32_e32 v29, 16, v184
	v_lshlrev_b32_e32 v31, 16, v185
	v_lshlrev_b32_e32 v33, 16, v186
	v_lshlrev_b32_e32 v37, 16, v187
	v_lshlrev_b32_e32 v34, 16, v188
	v_lshlrev_b32_e32 v35, 16, v189
	v_lshlrev_b32_e32 v38, 16, v190
	v_lshlrev_b32_e32 v39, 16, v195
	v_lshlrev_b32_e32 v40, 16, v197
	v_lshlrev_b32_e32 v43, 16, v198
	v_lshlrev_b32_e32 v42, 16, v199
	v_lshlrev_b32_e32 v45, 16, v200
	v_lshlrev_b32_e32 v44, 16, v201
	v_lshlrev_b32_e32 v46, 16, v203
	v_lshlrev_b32_e32 v49, 16, v204
	v_lshlrev_b32_e32 v48, 16, v205
	v_lshlrev_b32_e32 v41, 16, v196
	v_lshlrev_b32_e32 v47, 16, v202
	v_lshlrev_b32_e32 v51, 16, v206
	v_lshlrev_b32_e32 v50, 16, v207
	v_lshlrev_b32_e32 v53, 16, v191
	v_lshlrev_b32_e32 v52, 16, v193
	v_lshlrev_b32_e32 v55, 16, v192
	v_lshlrev_b32_e32 v54, 16, v194
	v_add_f32_e32 v88, v155, v35
	v_mul_f32_e32 v88, 0xbfb8aa3b, v88
	v_exp_f32_e32 v88, v88
	v_pk_add_f32 v[12:13], v[32:33], v[26:27] neg_lo:[0,1] neg_hi:[0,1]
	v_pk_add_f32 v[2:3], v[30:31], v[16:17] neg_lo:[0,1] neg_hi:[0,1]
	v_fma_f32 v13, v150, v13, v27
	v_add_f32_e32 v88, 1.0, v88
	v_rcp_f32_e32 v88, v88
	v_mul_f32_e32 v92, v157, v13
	v_fma_f32 v3, v149, v3, v17
	s_bitcmp1_b32 s3, 0
	v_mul_f32_e32 v89, 0xbf6002b1, v88
	v_cmp_gt_f32_e32 vcc, s85, v89
	s_cselect_b32 s8, 0x5000, 0
	v_mov_b32_e32 v94, v0
	v_cndmask_b32_e32 v89, 0, v239, vcc
	v_fmac_f32_e32 v89, 0xbf6002b1, v88
	v_exp_f32_e32 v88, v89
	v_cndmask_b32_e32 v89, 0, v236, vcc
	s_add_i32 s9, s8, 0
	s_mul_i32 s8, s3, 0xab
	v_ldexp_f32 v90, v88, v89
	v_add_f32_e32 v88, v154, v39
	v_mul_f32_e32 v88, 0xbfb8aa3b, v88
	v_exp_f32_e32 v88, v88
	v_mov_b32_e32 v89, v0
	s_bfe_u32 s8, s8, 0x70009
	s_mul_i32 s8, s8, 3
	v_add_f32_e32 v88, 1.0, v88
	v_rcp_f32_e32 v91, v88
	v_mul_f32_e32 v88, v92, v92
	s_sub_i32 s8, s3, s8
	s_and_b32 s8, s8, 0xff
	v_mov_b32_dpp v89, v88 quad_perm:[1,0,3,2] row_mask:0xf bank_mask:0xf
	v_fmac_f32_e32 v89, v92, v92
	s_mulk_i32 s8, 0x1100
	s_add_i32 s8, s8, 0
	v_add_f32_dpp v88, v89, v89 quad_perm:[2,3,0,1] row_mask:0xf bank_mask:0xf bound_ctrl:1
	v_pk_add_f32 v[14:15], v[36:37], v[28:29] neg_lo:[0,1] neg_hi:[0,1]
	s_nop 0
	v_add_f32_dpp v88, v88, v88 row_half_mirror row_mask:0xf bank_mask:0xf bound_ctrl:1
	v_fma_f32 v15, v151, v15, v29
	s_nop 0
	v_add_f32_dpp v88, v88, v88 row_mirror row_mask:0xf bank_mask:0xf bound_ctrl:1
	s_nop 0
	s_nop 1
	v_add_f32_dpp v88, v88, v88 row_bcast:15 row_mask:0xa bank_mask:0xf
	s_nop 1
	v_add_f32_dpp v88, v88, v88 row_bcast:31 row_mask:0xc bank_mask:0xf
	s_nop 0
	v_readlane_b32 s26, v88, 63
	s_nop 1
	v_mov_b32_e32 v88, s26
	v_add_f32_e32 v88, 0x2b8cbccc, v88
	v_cmp_gt_f32_e32 vcc, s82, v88
	v_mul_f32_e32 v89, 0x4b800000, v88
	s_nop 0
	v_cndmask_b32_e32 v88, v88, v89, vcc
	v_rsq_f32_e32 v88, v88
	s_nop 0
	v_mul_f32_e32 v89, 0x45800000, v88
	v_cndmask_b32_e32 v88, v88, v89, vcc
	v_add_f32_e32 v89, -1.0, v91
	v_fma_f32 v89, v158, v89, 1.0
	v_mul_f32_e32 v13, v89, v13
	v_mul_f32_e32 v89, v13, v3
	v_mul_f32_e32 v93, v156, v89
	v_mul_f32_e64 v88, v92, -v88
	s_nop 0
	v_mov_b32_dpp v94, v93 quad_perm:[1,0,3,2] row_mask:0xf bank_mask:0xf
	v_fmac_f32_e32 v94, v156, v89
	s_nop 1
	v_add_f32_dpp v89, v94, v94 quad_perm:[2,3,0,1] row_mask:0xf bank_mask:0xf bound_ctrl:1
	s_nop 1
	v_add_f32_dpp v89, v89, v89 row_half_mirror row_mask:0xf bank_mask:0xf bound_ctrl:1
	s_nop 1
	v_add_f32_dpp v89, v89, v89 row_mirror row_mask:0xf bank_mask:0xf bound_ctrl:1
	s_nop 0
	s_nop 1
	v_add_f32_dpp v89, v89, v89 row_bcast:15 row_mask:0xa bank_mask:0xf
	s_nop 1
	v_add_f32_dpp v89, v89, v89 row_bcast:31 row_mask:0xc bank_mask:0xf
	s_nop 0
	v_readlane_b32 s38, v89, 63
	v_add_u32_e32 v89, s9, v1
	ds_write2st64_b32 v89, v90, v88 offset1:16
	v_mul_f32_e64 v88, v91, -v88
	ds_write2st64_b32 v89, v88, v13 offset0:32 offset1:48
	ds_write_b32 v89, v3 offset:16384
	v_add_u32_e32 v3, s8, v1
	ds_write_b32 v3, v15 offset:40960
	s_and_saveexec_b64 s[50:51], s[44:45]
	s_cbranch_execz .LBB0_401
	s_lshl_b32 s24, s96, 2
	s_add_i32 s24, s8, s24
	v_mov_b32_e32 v13, s24
	v_mov_b32_e32 v3, s38
	ds_write_b32 v13, v3 offset:45056
